# pass 1: the second half's two histogram adds are issued at the start of the next stage, behind its fragment reads (no LDS atomics queued ahead of the reads after the barrier)
# baseline (speedup 1.0000x reference)
.LBB0_898:
	v_and_b32_e32 v99, 63, v186
	v_lshl_add_u32 v99, v99, 4, s96
	v_add_u32_e32 v141, s96, v73
	v_add_u32_e32 v142, s96, v75
	v_add_u32_e32 v143, s96, v120
	v_add_u32_e32 v144, s96, v121
	v_add_u32_e32 v145, s96, v122
	v_add_u32_e32 v146, s96, v123
	v_add_u32_e32 v147, s96, v124
	v_lshlrev_b32_e32 v61, 2, v196
	v_add_u32_e32 v61, 0x24800, v61
	v_mov_b32_e32 v155, v61
	s_mov_b32 s0, 0
	ds_read_b128 v[176:179], v99 offset:0
	ds_read_b128 v[180:183], v99 offset:4096
	ds_read_b128 v[230:233], v99 offset:1024
	ds_read_b128 v[234:237], v99 offset:5120
	ds_read_b128 v[238:241], v99 offset:2048
	ds_read_b128 v[242:245], v99 offset:6144
	ds_read_b128 v[246:249], v99 offset:3072
	ds_read_b128 v[50:53], v99 offset:7168
	s_waitcnt lgkmcnt(7)
	v_mfma_f32_32x32x16_bf16 v[0:15], v[34:37], v[176:179], 0
	s_waitcnt lgkmcnt(6)
	v_mfma_f32_32x32x16_bf16 v[160:175], v[34:37], v[180:183], 0
	s_waitcnt vmcnt(3)
	ds_write_b128 v140, v[16:19] offset:8192
	s_add_i32 s1, s0, 5
	s_min_i32 s1, s1, s14
	v_mad_i64_i32 v[184:185], s[2:3], s1, v193, v[116:117]
	global_load_dwordx4 v[16:19], v[184:185], off
	s_waitcnt lgkmcnt(6)
	v_mfma_f32_32x32x16_bf16 v[0:15], v[38:41], v[230:233], v[0:15]
	s_waitcnt lgkmcnt(5)
	v_mfma_f32_32x32x16_bf16 v[160:175], v[38:41], v[234:237], v[160:175]
	s_waitcnt lgkmcnt(4)
	v_mfma_f32_32x32x16_bf16 v[0:15], v[42:45], v[238:241], v[0:15]
	s_waitcnt lgkmcnt(3)
	v_mfma_f32_32x32x16_bf16 v[160:175], v[42:45], v[242:245], v[160:175]
	s_waitcnt lgkmcnt(2)
	v_mfma_f32_32x32x16_bf16 v[0:15], v[46:49], v[246:249], v[0:15]
	s_waitcnt lgkmcnt(1)
	v_mfma_f32_32x32x16_bf16 v[160:175], v[46:49], v[50:53], v[160:175]
	s_waitcnt lgkmcnt(0)
	s_barrier
	s_add_u32 s0, s0, 1
	s_cmp_ge_u32 s0, s13
	s_cbranch_scc1 .Lp1_drain0
.Lp1_c1:
	ds_read_b128 v[176:179], v99 offset:8192
	ds_read_b128 v[180:183], v99 offset:12288
	ds_read_b128 v[230:233], v99 offset:9216
	ds_read_b128 v[234:237], v99 offset:13312
	ds_read_b128 v[238:241], v99 offset:10240
	ds_read_b128 v[242:245], v99 offset:14336
	ds_read_b128 v[246:249], v99 offset:11264
	ds_read_b128 v[50:53], v99 offset:15360
	ds_add_u32 v61, v188
	ds_add_u32 v155, v188 offset:4096
	v_max_i32_e32 v56, 0, v8
	v_max_i32_e32 v57, 0, v0
	v_max_i32_e32 v60, 0, v9
	v_max_i32_e32 v61, 0, v1
	v_max_i32_e32 v64, 0, v10
	v_max_i32_e32 v65, 0, v2
	v_max_i32_e32 v154, 0, v11
	v_max_i32_e32 v155, 0, v3
	v_mul_f32_e32 v156, v100, v56
	v_mul_f32_e32 v157, v101, v57
	s_waitcnt lgkmcnt(9)
	v_mfma_f32_32x32x16_bf16 v[198:213], v[34:37], v[176:179], 0
	v_fmac_f32_e32 v156, v102, v60
	v_fmac_f32_e32 v157, v103, v61
	v_fmac_f32_e32 v156, v104, v64
	v_fmac_f32_e32 v157, v105, v65
	v_fmac_f32_e32 v156, v106, v154
	v_fmac_f32_e32 v157, v107, v155
	v_max_i32_e32 v56, 0, v12
	v_max_i32_e32 v57, 0, v4
	v_max_i32_e32 v60, 0, v13
	v_max_i32_e32 v61, 0, v5
	v_max_i32_e32 v64, 0, v14
	s_waitcnt lgkmcnt(8)
	v_mfma_f32_32x32x16_bf16 v[214:229], v[34:37], v[180:183], 0
	s_waitcnt vmcnt(3)
	ds_write_b128 v140, v[20:23]
	s_add_i32 s1, s0, 5
	s_min_i32 s1, s1, s14
	v_mad_i64_i32 v[184:185], s[2:3], s1, v193, v[116:117]
	global_load_dwordx4 v[20:23], v[184:185], off
	v_max_i32_e32 v65, 0, v6
	v_max_i32_e32 v154, 0, v15
	v_max_i32_e32 v155, 0, v7
	v_fmac_f32_e32 v156, v108, v56
	v_fmac_f32_e32 v157, v109, v57
	v_fmac_f32_e32 v156, v110, v60
	v_fmac_f32_e32 v157, v111, v61
	v_fmac_f32_e32 v156, v112, v64
	v_fmac_f32_e32 v157, v113, v65
	v_fmac_f32_e32 v156, v114, v154
	v_fmac_f32_e32 v157, v115, v155
	s_waitcnt lgkmcnt(8)
	v_mfma_f32_32x32x16_bf16 v[198:213], v[38:41], v[230:233], v[198:213]
	v_bfe_u32 v56, v157, 19, 12
	v_bfe_u32 v64, v156, 19, 12
	v_med3_u32 v56, v56, s94, v194
	v_med3_u32 v64, v64, s94, v194
	v_sub_u32_e32 v57, 0x86f, v56
	v_add_u32_e32 v60, 0xfffffb90, v56
	v_sub_u32_e32 v65, 0x86f, v64
	v_add_u32_e32 v154, 0xfffffb90, v64
	v_cmp_gt_f32_e32 vcc, 0, v157
	s_nop 1
	v_cndmask_b32_e32 v56, v60, v57, vcc
	s_waitcnt lgkmcnt(7)
	v_mfma_f32_32x32x16_bf16 v[214:229], v[38:41], v[234:237], v[214:229]
	v_cmp_gt_f32_e32 vcc, 0, v156
	v_lshl_add_u32 v61, v56, 2, v33
	ds_add_u32 v61, v188
	v_cndmask_b32_e32 v64, v154, v65, vcc
	v_lshl_add_u32 v155, v64, 2, v33
	ds_add_u32 v155, v188 offset:4096
	v_max_i32_e32 v56, 0, v168
	v_max_i32_e32 v57, 0, v160
	v_max_i32_e32 v60, 0, v169
	v_max_i32_e32 v61, 0, v161
	v_max_i32_e32 v64, 0, v170
	s_waitcnt lgkmcnt(8)
	v_mfma_f32_32x32x16_bf16 v[198:213], v[42:45], v[238:241], v[198:213]
	v_max_i32_e32 v65, 0, v162
	v_max_i32_e32 v154, 0, v171
	v_max_i32_e32 v155, 0, v163
	v_mul_f32_e32 v156, v100, v56
	v_mul_f32_e32 v157, v101, v57
	v_fmac_f32_e32 v156, v102, v60
	v_fmac_f32_e32 v157, v103, v61
	v_fmac_f32_e32 v156, v104, v64
	v_fmac_f32_e32 v157, v105, v65
	v_fmac_f32_e32 v156, v106, v154
	v_fmac_f32_e32 v157, v107, v155
	s_waitcnt lgkmcnt(7)
	v_mfma_f32_32x32x16_bf16 v[214:229], v[42:45], v[242:245], v[214:229]
	v_max_i32_e32 v56, 0, v172
	v_max_i32_e32 v57, 0, v164
	v_max_i32_e32 v60, 0, v173
	v_max_i32_e32 v61, 0, v165
	v_max_i32_e32 v64, 0, v174
	v_max_i32_e32 v65, 0, v166
	v_max_i32_e32 v154, 0, v175
	v_max_i32_e32 v155, 0, v167
	v_fmac_f32_e32 v156, v108, v56
	v_fmac_f32_e32 v157, v109, v57
	v_fmac_f32_e32 v156, v110, v60
	s_waitcnt lgkmcnt(6)
	v_mfma_f32_32x32x16_bf16 v[198:213], v[46:49], v[246:249], v[198:213]
	v_fmac_f32_e32 v157, v111, v61
	v_fmac_f32_e32 v156, v112, v64
	v_fmac_f32_e32 v157, v113, v65
	v_fmac_f32_e32 v156, v114, v154
	v_fmac_f32_e32 v157, v115, v155
	v_bfe_u32 v56, v157, 19, 12
	v_bfe_u32 v64, v156, 19, 12
	v_med3_u32 v56, v56, s94, v194
	v_med3_u32 v64, v64, s94, v194
	v_sub_u32_e32 v57, 0x86f, v56
	v_add_u32_e32 v60, 0xfffffb90, v56
	s_waitcnt lgkmcnt(5)
	v_mfma_f32_32x32x16_bf16 v[214:229], v[46:49], v[50:53], v[214:229]
	v_sub_u32_e32 v65, 0x86f, v64
	v_add_u32_e32 v154, 0xfffffb90, v64
	v_cmp_gt_f32_e32 vcc, 0, v157
	s_nop 1
	v_cndmask_b32_e32 v56, v60, v57, vcc
	v_cmp_gt_f32_e32 vcc, 0, v156
	v_lshl_add_u32 v61, v56, 2, v33
	v_cndmask_b32_e32 v64, v154, v65, vcc
	v_lshl_add_u32 v155, v64, 2, v33
	s_waitcnt lgkmcnt(2)
	s_barrier
	s_add_u32 s0, s0, 1
	s_cmp_ge_u32 s0, s13
	s_cbranch_scc1 .Lp1_drain1
.Lp1_c2:
	ds_read_b128 v[176:179], v99 offset:0
	ds_read_b128 v[180:183], v99 offset:4096
	ds_read_b128 v[230:233], v99 offset:1024
	ds_read_b128 v[234:237], v99 offset:5120
	ds_read_b128 v[238:241], v99 offset:2048
	ds_read_b128 v[242:245], v99 offset:6144
	ds_read_b128 v[246:249], v99 offset:3072
	ds_read_b128 v[50:53], v99 offset:7168
	ds_add_u32 v61, v188
	ds_add_u32 v155, v188 offset:4096
	v_max_i32_e32 v56, 0, v206
	v_max_i32_e32 v57, 0, v198
	v_max_i32_e32 v60, 0, v207
	v_max_i32_e32 v61, 0, v199
	v_max_i32_e32 v64, 0, v208
	v_max_i32_e32 v65, 0, v200
	v_max_i32_e32 v154, 0, v209
	v_max_i32_e32 v155, 0, v201
	v_mul_f32_e32 v156, v100, v56
	v_mul_f32_e32 v157, v101, v57
	s_waitcnt lgkmcnt(9)
	v_mfma_f32_32x32x16_bf16 v[0:15], v[34:37], v[176:179], 0
	v_fmac_f32_e32 v156, v102, v60
	v_fmac_f32_e32 v157, v103, v61
	v_fmac_f32_e32 v156, v104, v64
	v_fmac_f32_e32 v157, v105, v65
	v_fmac_f32_e32 v156, v106, v154
	v_fmac_f32_e32 v157, v107, v155
	v_max_i32_e32 v56, 0, v210
	v_max_i32_e32 v57, 0, v202
	v_max_i32_e32 v60, 0, v211
	v_max_i32_e32 v61, 0, v203
	v_max_i32_e32 v64, 0, v212
	s_waitcnt lgkmcnt(8)
	v_mfma_f32_32x32x16_bf16 v[160:175], v[34:37], v[180:183], 0
	s_waitcnt vmcnt(3)
	ds_write_b128 v140, v[24:27] offset:8192
	s_add_i32 s1, s0, 5
	s_min_i32 s1, s1, s14
	v_mad_i64_i32 v[184:185], s[2:3], s1, v193, v[116:117]
	global_load_dwordx4 v[24:27], v[184:185], off
	v_max_i32_e32 v65, 0, v204
	v_max_i32_e32 v154, 0, v213
	v_max_i32_e32 v155, 0, v205
	v_fmac_f32_e32 v156, v108, v56
	v_fmac_f32_e32 v157, v109, v57
	v_fmac_f32_e32 v156, v110, v60
	v_fmac_f32_e32 v157, v111, v61
	v_fmac_f32_e32 v156, v112, v64
	v_fmac_f32_e32 v157, v113, v65
	v_fmac_f32_e32 v156, v114, v154
	v_fmac_f32_e32 v157, v115, v155
	s_waitcnt lgkmcnt(8)
	v_mfma_f32_32x32x16_bf16 v[0:15], v[38:41], v[230:233], v[0:15]
	v_bfe_u32 v56, v157, 19, 12
	v_bfe_u32 v64, v156, 19, 12
	v_med3_u32 v56, v56, s94, v194
	v_med3_u32 v64, v64, s94, v194
	v_sub_u32_e32 v57, 0x86f, v56
	v_add_u32_e32 v60, 0xfffffb90, v56
	v_sub_u32_e32 v65, 0x86f, v64
	v_add_u32_e32 v154, 0xfffffb90, v64
	v_cmp_gt_f32_e32 vcc, 0, v157
	s_nop 1
	v_cndmask_b32_e32 v56, v60, v57, vcc
	s_waitcnt lgkmcnt(7)
	v_mfma_f32_32x32x16_bf16 v[160:175], v[38:41], v[234:237], v[160:175]
	v_cmp_gt_f32_e32 vcc, 0, v156
	v_lshl_add_u32 v61, v56, 2, v33
	ds_add_u32 v61, v188
	v_cndmask_b32_e32 v64, v154, v65, vcc
	v_lshl_add_u32 v155, v64, 2, v33
	ds_add_u32 v155, v188 offset:4096
	v_max_i32_e32 v56, 0, v222
	v_max_i32_e32 v57, 0, v214
	v_max_i32_e32 v60, 0, v223
	v_max_i32_e32 v61, 0, v215
	v_max_i32_e32 v64, 0, v224
	s_waitcnt lgkmcnt(8)
	v_mfma_f32_32x32x16_bf16 v[0:15], v[42:45], v[238:241], v[0:15]
	v_max_i32_e32 v65, 0, v216
	v_max_i32_e32 v154, 0, v225
	v_max_i32_e32 v155, 0, v217
	v_mul_f32_e32 v156, v100, v56
	v_mul_f32_e32 v157, v101, v57
	v_fmac_f32_e32 v156, v102, v60
	v_fmac_f32_e32 v157, v103, v61
	v_fmac_f32_e32 v156, v104, v64
	v_fmac_f32_e32 v157, v105, v65
	v_fmac_f32_e32 v156, v106, v154
	v_fmac_f32_e32 v157, v107, v155
	s_waitcnt lgkmcnt(7)
	v_mfma_f32_32x32x16_bf16 v[160:175], v[42:45], v[242:245], v[160:175]
	v_max_i32_e32 v56, 0, v226
	v_max_i32_e32 v57, 0, v218
	v_max_i32_e32 v60, 0, v227
	v_max_i32_e32 v61, 0, v219
	v_max_i32_e32 v64, 0, v228
	v_max_i32_e32 v65, 0, v220
	v_max_i32_e32 v154, 0, v229
	v_max_i32_e32 v155, 0, v221
	v_fmac_f32_e32 v156, v108, v56
	v_fmac_f32_e32 v157, v109, v57
	v_fmac_f32_e32 v156, v110, v60
	s_waitcnt lgkmcnt(6)
	v_mfma_f32_32x32x16_bf16 v[0:15], v[46:49], v[246:249], v[0:15]
	v_fmac_f32_e32 v157, v111, v61
	v_fmac_f32_e32 v156, v112, v64
	v_fmac_f32_e32 v157, v113, v65
	v_fmac_f32_e32 v156, v114, v154
	v_fmac_f32_e32 v157, v115, v155
	v_bfe_u32 v56, v157, 19, 12
	v_bfe_u32 v64, v156, 19, 12
	v_med3_u32 v56, v56, s94, v194
	v_med3_u32 v64, v64, s94, v194
	v_sub_u32_e32 v57, 0x86f, v56
	v_add_u32_e32 v60, 0xfffffb90, v56
	s_waitcnt lgkmcnt(5)
	v_mfma_f32_32x32x16_bf16 v[160:175], v[46:49], v[50:53], v[160:175]
	v_sub_u32_e32 v65, 0x86f, v64
	v_add_u32_e32 v154, 0xfffffb90, v64
	v_cmp_gt_f32_e32 vcc, 0, v157
	s_nop 1
	v_cndmask_b32_e32 v56, v60, v57, vcc
	v_cmp_gt_f32_e32 vcc, 0, v156
	v_lshl_add_u32 v61, v56, 2, v33
	v_cndmask_b32_e32 v64, v154, v65, vcc
	v_lshl_add_u32 v155, v64, 2, v33
	s_waitcnt lgkmcnt(2)
	s_barrier
	s_add_u32 s0, s0, 1
	s_cmp_ge_u32 s0, s13
	s_cbranch_scc1 .Lp1_drain0
.Lp1_c3:
	ds_read_b128 v[176:179], v99 offset:8192
	ds_read_b128 v[180:183], v99 offset:12288
	ds_read_b128 v[230:233], v99 offset:9216
	ds_read_b128 v[234:237], v99 offset:13312
	ds_read_b128 v[238:241], v99 offset:10240
	ds_read_b128 v[242:245], v99 offset:14336
	ds_read_b128 v[246:249], v99 offset:11264
	ds_read_b128 v[50:53], v99 offset:15360
	ds_add_u32 v61, v188
	ds_add_u32 v155, v188 offset:4096
	v_max_i32_e32 v56, 0, v8
	v_max_i32_e32 v57, 0, v0
	v_max_i32_e32 v60, 0, v9
	v_max_i32_e32 v61, 0, v1
	v_max_i32_e32 v64, 0, v10
	v_max_i32_e32 v65, 0, v2
	v_max_i32_e32 v154, 0, v11
	v_max_i32_e32 v155, 0, v3
	v_mul_f32_e32 v156, v100, v56
	v_mul_f32_e32 v157, v101, v57
	s_waitcnt lgkmcnt(9)
	v_mfma_f32_32x32x16_bf16 v[198:213], v[34:37], v[176:179], 0
	v_fmac_f32_e32 v156, v102, v60
	v_fmac_f32_e32 v157, v103, v61
	v_fmac_f32_e32 v156, v104, v64
	v_fmac_f32_e32 v157, v105, v65
	v_fmac_f32_e32 v156, v106, v154
	v_fmac_f32_e32 v157, v107, v155
	v_max_i32_e32 v56, 0, v12
	v_max_i32_e32 v57, 0, v4
	v_max_i32_e32 v60, 0, v13
	v_max_i32_e32 v61, 0, v5
	v_max_i32_e32 v64, 0, v14
	s_waitcnt lgkmcnt(8)
	v_mfma_f32_32x32x16_bf16 v[214:229], v[34:37], v[180:183], 0
	s_waitcnt vmcnt(3)
	ds_write_b128 v140, v[28:31]
	s_add_i32 s1, s0, 5
	s_min_i32 s1, s1, s14
	v_mad_i64_i32 v[184:185], s[2:3], s1, v193, v[116:117]
	global_load_dwordx4 v[28:31], v[184:185], off
	v_max_i32_e32 v65, 0, v6
	v_max_i32_e32 v154, 0, v15
	v_max_i32_e32 v155, 0, v7
	v_fmac_f32_e32 v156, v108, v56
	v_fmac_f32_e32 v157, v109, v57
	v_fmac_f32_e32 v156, v110, v60
	v_fmac_f32_e32 v157, v111, v61
	v_fmac_f32_e32 v156, v112, v64
	v_fmac_f32_e32 v157, v113, v65
	v_fmac_f32_e32 v156, v114, v154
	v_fmac_f32_e32 v157, v115, v155
	s_waitcnt lgkmcnt(8)
	v_mfma_f32_32x32x16_bf16 v[198:213], v[38:41], v[230:233], v[198:213]
	v_bfe_u32 v56, v157, 19, 12
	v_bfe_u32 v64, v156, 19, 12
	v_med3_u32 v56, v56, s94, v194
	v_med3_u32 v64, v64, s94, v194
	v_sub_u32_e32 v57, 0x86f, v56
	v_add_u32_e32 v60, 0xfffffb90, v56
	v_sub_u32_e32 v65, 0x86f, v64
	v_add_u32_e32 v154, 0xfffffb90, v64
	v_cmp_gt_f32_e32 vcc, 0, v157
	s_nop 1
	v_cndmask_b32_e32 v56, v60, v57, vcc
	s_waitcnt lgkmcnt(7)
	v_mfma_f32_32x32x16_bf16 v[214:229], v[38:41], v[234:237], v[214:229]
	v_cmp_gt_f32_e32 vcc, 0, v156
	v_lshl_add_u32 v61, v56, 2, v33
	ds_add_u32 v61, v188
	v_cndmask_b32_e32 v64, v154, v65, vcc
	v_lshl_add_u32 v155, v64, 2, v33
	ds_add_u32 v155, v188 offset:4096
	v_max_i32_e32 v56, 0, v168
	v_max_i32_e32 v57, 0, v160
	v_max_i32_e32 v60, 0, v169
	v_max_i32_e32 v61, 0, v161
	v_max_i32_e32 v64, 0, v170
	s_waitcnt lgkmcnt(8)
	v_mfma_f32_32x32x16_bf16 v[198:213], v[42:45], v[238:241], v[198:213]
	v_max_i32_e32 v65, 0, v162
	v_max_i32_e32 v154, 0, v171
	v_max_i32_e32 v155, 0, v163
	v_mul_f32_e32 v156, v100, v56
	v_mul_f32_e32 v157, v101, v57
	v_fmac_f32_e32 v156, v102, v60
	v_fmac_f32_e32 v157, v103, v61
	v_fmac_f32_e32 v156, v104, v64
	v_fmac_f32_e32 v157, v105, v65
	v_fmac_f32_e32 v156, v106, v154
	v_fmac_f32_e32 v157, v107, v155
	s_waitcnt lgkmcnt(7)
	v_mfma_f32_32x32x16_bf16 v[214:229], v[42:45], v[242:245], v[214:229]
	v_max_i32_e32 v56, 0, v172
	v_max_i32_e32 v57, 0, v164
	v_max_i32_e32 v60, 0, v173
	v_max_i32_e32 v61, 0, v165
	v_max_i32_e32 v64, 0, v174
	v_max_i32_e32 v65, 0, v166
	v_max_i32_e32 v154, 0, v175
	v_max_i32_e32 v155, 0, v167
	v_fmac_f32_e32 v156, v108, v56
	v_fmac_f32_e32 v157, v109, v57
	v_fmac_f32_e32 v156, v110, v60
	s_waitcnt lgkmcnt(6)
	v_mfma_f32_32x32x16_bf16 v[198:213], v[46:49], v[246:249], v[198:213]
	v_fmac_f32_e32 v157, v111, v61
	v_fmac_f32_e32 v156, v112, v64
	v_fmac_f32_e32 v157, v113, v65
	v_fmac_f32_e32 v156, v114, v154
	v_fmac_f32_e32 v157, v115, v155
	v_bfe_u32 v56, v157, 19, 12
	v_bfe_u32 v64, v156, 19, 12
	v_med3_u32 v56, v56, s94, v194
	v_med3_u32 v64, v64, s94, v194
	v_sub_u32_e32 v57, 0x86f, v56
	v_add_u32_e32 v60, 0xfffffb90, v56
	s_waitcnt lgkmcnt(5)
	v_mfma_f32_32x32x16_bf16 v[214:229], v[46:49], v[50:53], v[214:229]
	v_sub_u32_e32 v65, 0x86f, v64
	v_add_u32_e32 v154, 0xfffffb90, v64
	v_cmp_gt_f32_e32 vcc, 0, v157
	s_nop 1
	v_cndmask_b32_e32 v56, v60, v57, vcc
	v_cmp_gt_f32_e32 vcc, 0, v156
	v_lshl_add_u32 v61, v56, 2, v33
	v_cndmask_b32_e32 v64, v154, v65, vcc
	v_lshl_add_u32 v155, v64, 2, v33
	s_waitcnt lgkmcnt(2)
	s_barrier
	s_add_u32 s0, s0, 1
	s_cmp_ge_u32 s0, s13
	s_cbranch_scc1 .Lp1_drain1
.Lp1_c0:
	ds_read_b128 v[176:179], v99 offset:0
	ds_read_b128 v[180:183], v99 offset:4096
	ds_read_b128 v[230:233], v99 offset:1024
	ds_read_b128 v[234:237], v99 offset:5120
	ds_read_b128 v[238:241], v99 offset:2048
	ds_read_b128 v[242:245], v99 offset:6144
	ds_read_b128 v[246:249], v99 offset:3072
	ds_read_b128 v[50:53], v99 offset:7168
	ds_add_u32 v61, v188
	ds_add_u32 v155, v188 offset:4096
	v_max_i32_e32 v56, 0, v206
	v_max_i32_e32 v57, 0, v198
	v_max_i32_e32 v60, 0, v207
	v_max_i32_e32 v61, 0, v199
	v_max_i32_e32 v64, 0, v208
	v_max_i32_e32 v65, 0, v200
	v_max_i32_e32 v154, 0, v209
	v_max_i32_e32 v155, 0, v201
	v_mul_f32_e32 v156, v100, v56
	v_mul_f32_e32 v157, v101, v57
	s_waitcnt lgkmcnt(9)
	v_mfma_f32_32x32x16_bf16 v[0:15], v[34:37], v[176:179], 0
	v_fmac_f32_e32 v156, v102, v60
	v_fmac_f32_e32 v157, v103, v61
	v_fmac_f32_e32 v156, v104, v64
	v_fmac_f32_e32 v157, v105, v65
	v_fmac_f32_e32 v156, v106, v154
	v_fmac_f32_e32 v157, v107, v155
	v_max_i32_e32 v56, 0, v210
	v_max_i32_e32 v57, 0, v202
	v_max_i32_e32 v60, 0, v211
	v_max_i32_e32 v61, 0, v203
	v_max_i32_e32 v64, 0, v212
	s_waitcnt lgkmcnt(8)
	v_mfma_f32_32x32x16_bf16 v[160:175], v[34:37], v[180:183], 0
	s_waitcnt vmcnt(3)
	ds_write_b128 v140, v[16:19] offset:8192
	s_add_i32 s1, s0, 5
	s_min_i32 s1, s1, s14
	v_mad_i64_i32 v[184:185], s[2:3], s1, v193, v[116:117]
	global_load_dwordx4 v[16:19], v[184:185], off
	v_max_i32_e32 v65, 0, v204
	v_max_i32_e32 v154, 0, v213
	v_max_i32_e32 v155, 0, v205
	v_fmac_f32_e32 v156, v108, v56
	v_fmac_f32_e32 v157, v109, v57
	v_fmac_f32_e32 v156, v110, v60
	v_fmac_f32_e32 v157, v111, v61
	v_fmac_f32_e32 v156, v112, v64
	v_fmac_f32_e32 v157, v113, v65
	v_fmac_f32_e32 v156, v114, v154
	v_fmac_f32_e32 v157, v115, v155
	s_waitcnt lgkmcnt(8)
	v_mfma_f32_32x32x16_bf16 v[0:15], v[38:41], v[230:233], v[0:15]
	v_bfe_u32 v56, v157, 19, 12
	v_bfe_u32 v64, v156, 19, 12
	v_med3_u32 v56, v56, s94, v194
	v_med3_u32 v64, v64, s94, v194
	v_sub_u32_e32 v57, 0x86f, v56
	v_add_u32_e32 v60, 0xfffffb90, v56
	v_sub_u32_e32 v65, 0x86f, v64
	v_add_u32_e32 v154, 0xfffffb90, v64
	v_cmp_gt_f32_e32 vcc, 0, v157
	s_nop 1
	v_cndmask_b32_e32 v56, v60, v57, vcc
	s_waitcnt lgkmcnt(7)
	v_mfma_f32_32x32x16_bf16 v[160:175], v[38:41], v[234:237], v[160:175]
	v_cmp_gt_f32_e32 vcc, 0, v156
	v_lshl_add_u32 v61, v56, 2, v33
	ds_add_u32 v61, v188
	v_cndmask_b32_e32 v64, v154, v65, vcc
	v_lshl_add_u32 v155, v64, 2, v33
	ds_add_u32 v155, v188 offset:4096
	v_max_i32_e32 v56, 0, v222
	v_max_i32_e32 v57, 0, v214
	v_max_i32_e32 v60, 0, v223
	v_max_i32_e32 v61, 0, v215
	v_max_i32_e32 v64, 0, v224
	s_waitcnt lgkmcnt(8)
	v_mfma_f32_32x32x16_bf16 v[0:15], v[42:45], v[238:241], v[0:15]
	v_max_i32_e32 v65, 0, v216
	v_max_i32_e32 v154, 0, v225
	v_max_i32_e32 v155, 0, v217
	v_mul_f32_e32 v156, v100, v56
	v_mul_f32_e32 v157, v101, v57
	v_fmac_f32_e32 v156, v102, v60
	v_fmac_f32_e32 v157, v103, v61
	v_fmac_f32_e32 v156, v104, v64
	v_fmac_f32_e32 v157, v105, v65
	v_fmac_f32_e32 v156, v106, v154
	v_fmac_f32_e32 v157, v107, v155
	s_waitcnt lgkmcnt(7)
	v_mfma_f32_32x32x16_bf16 v[160:175], v[42:45], v[242:245], v[160:175]
	v_max_i32_e32 v56, 0, v226
	v_max_i32_e32 v57, 0, v218
	v_max_i32_e32 v60, 0, v227
	v_max_i32_e32 v61, 0, v219
	v_max_i32_e32 v64, 0, v228
	v_max_i32_e32 v65, 0, v220
	v_max_i32_e32 v154, 0, v229
	v_max_i32_e32 v155, 0, v221
	v_fmac_f32_e32 v156, v108, v56
	v_fmac_f32_e32 v157, v109, v57
	v_fmac_f32_e32 v156, v110, v60
	s_waitcnt lgkmcnt(6)
	v_mfma_f32_32x32x16_bf16 v[0:15], v[46:49], v[246:249], v[0:15]
	v_fmac_f32_e32 v157, v111, v61
	v_fmac_f32_e32 v156, v112, v64
	v_fmac_f32_e32 v157, v113, v65
	v_fmac_f32_e32 v156, v114, v154
	v_fmac_f32_e32 v157, v115, v155
	v_bfe_u32 v56, v157, 19, 12
	v_bfe_u32 v64, v156, 19, 12
	v_med3_u32 v56, v56, s94, v194
	v_med3_u32 v64, v64, s94, v194
	v_sub_u32_e32 v57, 0x86f, v56
	v_add_u32_e32 v60, 0xfffffb90, v56
	s_waitcnt lgkmcnt(5)
	v_mfma_f32_32x32x16_bf16 v[160:175], v[46:49], v[50:53], v[160:175]
	v_sub_u32_e32 v65, 0x86f, v64
	v_add_u32_e32 v154, 0xfffffb90, v64
	v_cmp_gt_f32_e32 vcc, 0, v157
	s_nop 1
	v_cndmask_b32_e32 v56, v60, v57, vcc
	v_cmp_gt_f32_e32 vcc, 0, v156
	v_lshl_add_u32 v61, v56, 2, v33
	v_cndmask_b32_e32 v64, v154, v65, vcc
	v_lshl_add_u32 v155, v64, 2, v33
	s_waitcnt lgkmcnt(2)
	s_barrier
	s_add_u32 s0, s0, 1
	s_cmp_ge_u32 s0, s13
	s_cbranch_scc1 .Lp1_drain0
	s_branch .Lp1_c1
.Lp1_drain0:
	ds_add_u32 v61, v188
	ds_add_u32 v155, v188 offset:4096
	v_max_i32_e32 v56, 0, v8
	v_max_i32_e32 v57, 0, v0
	v_max_i32_e32 v60, 0, v9
	v_max_i32_e32 v61, 0, v1
	v_max_i32_e32 v64, 0, v10
	v_max_i32_e32 v65, 0, v2
	v_max_i32_e32 v154, 0, v11
	v_max_i32_e32 v155, 0, v3
	v_mul_f32_e32 v156, v100, v56
	v_mul_f32_e32 v157, v101, v57
	v_fmac_f32_e32 v156, v102, v60
	v_fmac_f32_e32 v157, v103, v61
	v_fmac_f32_e32 v156, v104, v64
	v_fmac_f32_e32 v157, v105, v65
	v_fmac_f32_e32 v156, v106, v154
	v_fmac_f32_e32 v157, v107, v155
	v_max_i32_e32 v56, 0, v12
	v_max_i32_e32 v57, 0, v4
	v_max_i32_e32 v60, 0, v13
	v_max_i32_e32 v61, 0, v5
	v_max_i32_e32 v64, 0, v14
	v_max_i32_e32 v65, 0, v6
	v_max_i32_e32 v154, 0, v15
	v_max_i32_e32 v155, 0, v7
	v_fmac_f32_e32 v156, v108, v56
	v_fmac_f32_e32 v157, v109, v57
	v_fmac_f32_e32 v156, v110, v60
	v_fmac_f32_e32 v157, v111, v61
	v_fmac_f32_e32 v156, v112, v64
	v_fmac_f32_e32 v157, v113, v65
	v_fmac_f32_e32 v156, v114, v154
	v_fmac_f32_e32 v157, v115, v155
	v_bfe_u32 v56, v157, 19, 12
	v_bfe_u32 v64, v156, 19, 12
	v_med3_u32 v56, v56, s94, v194
	v_med3_u32 v64, v64, s94, v194
	v_sub_u32_e32 v57, 0x86f, v56
	v_add_u32_e32 v60, 0xfffffb90, v56
	v_sub_u32_e32 v65, 0x86f, v64
	v_add_u32_e32 v154, 0xfffffb90, v64
	v_cmp_gt_f32_e32 vcc, 0, v157
	s_nop 1
	v_cndmask_b32_e32 v56, v60, v57, vcc
	v_cmp_gt_f32_e32 vcc, 0, v156
	v_lshl_add_u32 v61, v56, 2, v33
	ds_add_u32 v61, v188
	v_cndmask_b32_e32 v64, v154, v65, vcc
	v_lshl_add_u32 v155, v64, 2, v33
	ds_add_u32 v155, v188 offset:4096
	v_max_i32_e32 v56, 0, v168
	v_max_i32_e32 v57, 0, v160
	v_max_i32_e32 v60, 0, v169
	v_max_i32_e32 v61, 0, v161
	v_max_i32_e32 v64, 0, v170
	v_max_i32_e32 v65, 0, v162
	v_max_i32_e32 v154, 0, v171
	v_max_i32_e32 v155, 0, v163
	v_mul_f32_e32 v156, v100, v56
	v_mul_f32_e32 v157, v101, v57
	v_fmac_f32_e32 v156, v102, v60
	v_fmac_f32_e32 v157, v103, v61
	v_fmac_f32_e32 v156, v104, v64
	v_fmac_f32_e32 v157, v105, v65
	v_fmac_f32_e32 v156, v106, v154
	v_fmac_f32_e32 v157, v107, v155
	v_max_i32_e32 v56, 0, v172
	v_max_i32_e32 v57, 0, v164
	v_max_i32_e32 v60, 0, v173
	v_max_i32_e32 v61, 0, v165
	v_max_i32_e32 v64, 0, v174
	v_max_i32_e32 v65, 0, v166
	v_max_i32_e32 v154, 0, v175
	v_max_i32_e32 v155, 0, v167
	v_fmac_f32_e32 v156, v108, v56
	v_fmac_f32_e32 v157, v109, v57
	v_fmac_f32_e32 v156, v110, v60
	v_fmac_f32_e32 v157, v111, v61
	v_fmac_f32_e32 v156, v112, v64
	v_fmac_f32_e32 v157, v113, v65
	v_fmac_f32_e32 v156, v114, v154
	v_fmac_f32_e32 v157, v115, v155
	v_bfe_u32 v56, v157, 19, 12
	v_bfe_u32 v64, v156, 19, 12
	v_med3_u32 v56, v56, s94, v194
	v_med3_u32 v64, v64, s94, v194
	v_sub_u32_e32 v57, 0x86f, v56
	v_add_u32_e32 v60, 0xfffffb90, v56
	v_sub_u32_e32 v65, 0x86f, v64
	v_add_u32_e32 v154, 0xfffffb90, v64
	v_cmp_gt_f32_e32 vcc, 0, v157
	s_nop 1
	v_cndmask_b32_e32 v56, v60, v57, vcc
	v_cmp_gt_f32_e32 vcc, 0, v156
	v_lshl_add_u32 v61, v56, 2, v33
	ds_add_u32 v61, v188
	v_cndmask_b32_e32 v64, v154, v65, vcc
	v_lshl_add_u32 v155, v64, 2, v33
	ds_add_u32 v155, v188 offset:4096
	s_branch .LBB0_904
.Lp1_drain1:
	ds_add_u32 v61, v188
	ds_add_u32 v155, v188 offset:4096
	v_max_i32_e32 v56, 0, v206
	v_max_i32_e32 v57, 0, v198
	v_max_i32_e32 v60, 0, v207
	v_max_i32_e32 v61, 0, v199
	v_max_i32_e32 v64, 0, v208
	v_max_i32_e32 v65, 0, v200
	v_max_i32_e32 v154, 0, v209
	v_max_i32_e32 v155, 0, v201
	v_mul_f32_e32 v156, v100, v56
	v_mul_f32_e32 v157, v101, v57
	v_fmac_f32_e32 v156, v102, v60
	v_fmac_f32_e32 v157, v103, v61
	v_fmac_f32_e32 v156, v104, v64
	v_fmac_f32_e32 v157, v105, v65
	v_fmac_f32_e32 v156, v106, v154
	v_fmac_f32_e32 v157, v107, v155
	v_max_i32_e32 v56, 0, v210
	v_max_i32_e32 v57, 0, v202
	v_max_i32_e32 v60, 0, v211
	v_max_i32_e32 v61, 0, v203
	v_max_i32_e32 v64, 0, v212
	v_max_i32_e32 v65, 0, v204
	v_max_i32_e32 v154, 0, v213
	v_max_i32_e32 v155, 0, v205
	v_fmac_f32_e32 v156, v108, v56
	v_fmac_f32_e32 v157, v109, v57
	v_fmac_f32_e32 v156, v110, v60
	v_fmac_f32_e32 v157, v111, v61
	v_fmac_f32_e32 v156, v112, v64
	v_fmac_f32_e32 v157, v113, v65
	v_fmac_f32_e32 v156, v114, v154
	v_fmac_f32_e32 v157, v115, v155
	v_bfe_u32 v56, v157, 19, 12
	v_bfe_u32 v64, v156, 19, 12
	v_med3_u32 v56, v56, s94, v194
	v_med3_u32 v64, v64, s94, v194
	v_sub_u32_e32 v57, 0x86f, v56
	v_add_u32_e32 v60, 0xfffffb90, v56
	v_sub_u32_e32 v65, 0x86f, v64
	v_add_u32_e32 v154, 0xfffffb90, v64
	v_cmp_gt_f32_e32 vcc, 0, v157
	s_nop 1
	v_cndmask_b32_e32 v56, v60, v57, vcc
	v_cmp_gt_f32_e32 vcc, 0, v156
	v_lshl_add_u32 v61, v56, 2, v33
	ds_add_u32 v61, v188
	v_cndmask_b32_e32 v64, v154, v65, vcc
	v_lshl_add_u32 v155, v64, 2, v33
	ds_add_u32 v155, v188 offset:4096
	v_max_i32_e32 v56, 0, v222
	v_max_i32_e32 v57, 0, v214
	v_max_i32_e32 v60, 0, v223
	v_max_i32_e32 v61, 0, v215
	v_max_i32_e32 v64, 0, v224
	v_max_i32_e32 v65, 0, v216
	v_max_i32_e32 v154, 0, v225
	v_max_i32_e32 v155, 0, v217
	v_mul_f32_e32 v156, v100, v56
	v_mul_f32_e32 v157, v101, v57
	v_fmac_f32_e32 v156, v102, v60
	v_fmac_f32_e32 v157, v103, v61
	v_fmac_f32_e32 v156, v104, v64
	v_fmac_f32_e32 v157, v105, v65
	v_fmac_f32_e32 v156, v106, v154
	v_fmac_f32_e32 v157, v107, v155
	v_max_i32_e32 v56, 0, v226
	v_max_i32_e32 v57, 0, v218
	v_max_i32_e32 v60, 0, v227
	v_max_i32_e32 v61, 0, v219
	v_max_i32_e32 v64, 0, v228
	v_max_i32_e32 v65, 0, v220
	v_max_i32_e32 v154, 0, v229
	v_max_i32_e32 v155, 0, v221
	v_fmac_f32_e32 v156, v108, v56
	v_fmac_f32_e32 v157, v109, v57
	v_fmac_f32_e32 v156, v110, v60
	v_fmac_f32_e32 v157, v111, v61
	v_fmac_f32_e32 v156, v112, v64
	v_fmac_f32_e32 v157, v113, v65
	v_fmac_f32_e32 v156, v114, v154
	v_fmac_f32_e32 v157, v115, v155
	v_bfe_u32 v56, v157, 19, 12
	v_bfe_u32 v64, v156, 19, 12
	v_med3_u32 v56, v56, s94, v194
	v_med3_u32 v64, v64, s94, v194
	v_sub_u32_e32 v57, 0x86f, v56
	v_add_u32_e32 v60, 0xfffffb90, v56
	v_sub_u32_e32 v65, 0x86f, v64
	v_add_u32_e32 v154, 0xfffffb90, v64
	v_cmp_gt_f32_e32 vcc, 0, v157
	s_nop 1
	v_cndmask_b32_e32 v56, v60, v57, vcc
	v_cmp_gt_f32_e32 vcc, 0, v156
	v_lshl_add_u32 v61, v56, 2, v33
	ds_add_u32 v61, v188
	v_cndmask_b32_e32 v64, v154, v65, vcc
	v_lshl_add_u32 v155, v64, 2, v33
	ds_add_u32 v155, v188 offset:4096
	s_branch .LBB0_904
